# phase 15 (transpose back) rewritten by hand: fully unrolled over the block's 8 tiles, rows requested two tiles ahead, v_perm_b32 interleave; same LDS image and barriers
# speedup vs baseline: 1.0039x; 1.0039x over previous
.LBB0_181:
	s_andn2_b64 vcc, exec, s[0:1]
	s_cbranch_vccnz .LBB0_299
	s_cmp_lt_i32 s86, 13
	s_mov_b64 s[0:1], -1
	s_cbranch_scc1 .LBB0_273
	s_cmp_lt_i32 s86, 14
	s_cbranch_scc1 .LBB0_239
	s_cmp_gt_i32 s86, 14
	s_cbranch_scc0 .LBB0_195
	v_readlane_b32 s4, v249, 14
	v_readlane_b32 s5, v249, 15
	v_readlane_b32 s10, v250, 4
	s_waitcnt vmcnt(0) lgkmcnt(0)
	s_lshr_b32 s10, s10, 9
	s_and_b32 s14, s10, 7
	s_lshr_b32 s15, s10, 3
	s_mov_b32 s12, 0x05040100
	s_mov_b32 s13, 0x07060302
	v_and_b32_e32 v63, 15, v163
	v_lshrrev_b32_e32 v49, 4, v163
	v_lshlrev_b32_e32 v48, 14, v49
	v_lshl_add_u32 v48, v63, 4, v48
	v_lshlrev_b32_e32 v62, 12, v49
	v_lshl_add_u32 v62, v63, 4, v62
	v_lshrrev_b32_e32 v56, 3, v49
	v_add3_u32 v56, v56, v63, 0
	v_and_b32_e32 v56, 15, v56
	v_lshlrev_b32_e32 v56, 4, v56
	v_lshl_add_u32 v56, v49, 8, v56
	v_lshrrev_b32_e32 v57, 3, v49
	v_add3_u32 v57, v57, v63, 4
	v_and_b32_e32 v57, 15, v57
	v_lshlrev_b32_e32 v57, 4, v57
	v_lshl_add_u32 v57, v49, 8, v57
	v_add_u32_e32 v57, 0x2000, v57
	v_lshrrev_b32_e32 v58, 3, v49
	v_add3_u32 v58, v58, v63, 8
	v_and_b32_e32 v58, 15, v58
	v_lshlrev_b32_e32 v58, 4, v58
	v_lshl_add_u32 v58, v49, 8, v58
	v_add_u32_e32 v58, 0x4000, v58
	v_lshrrev_b32_e32 v59, 3, v49
	v_add3_u32 v59, v59, v63, 12
	v_and_b32_e32 v59, 15, v59
	v_lshlrev_b32_e32 v59, 4, v59
	v_lshl_add_u32 v59, v49, 8, v59
	v_add_u32_e32 v59, 0x6000, v59
	v_lshl_add_u32 v60, v63, 2, v49
	v_and_b32_e32 v60, 63, v60
	v_lshlrev_b32_e32 v60, 2, v60
	v_lshl_add_u32 v60, v63, 11, v60
	v_lshl_add_u32 v61, v63, 2, v49
	v_add_u32_e32 v61, 32, v61
	v_and_b32_e32 v61, 63, v61
	v_lshlrev_b32_e32 v61, 2, v61
	v_lshl_add_u32 v61, v63, 11, v61
	s_add_i32 s2, s15, 0
	s_lshl_b32 s3, s2, 8
	s_lshl_b32 s16, s14, 21
	s_add_u32 s16, s16, s3
	s_add_u32 s16, s16, 0x14000000
	s_add_u32 s6, s4, s16
	s_addc_u32 s7, s5, 0
	global_load_dwordx4 v[0:3], v48, s[6:7]
	s_add_u32 s6, s6, 0x80000
	s_addc_u32 s7, s7, 0
	global_load_dwordx4 v[4:7], v48, s[6:7]
	s_add_u32 s6, s6, 0x80000
	s_addc_u32 s7, s7, 0
	global_load_dwordx4 v[8:11], v48, s[6:7]
	s_add_u32 s6, s6, 0x80000
	s_addc_u32 s7, s7, 0
	global_load_dwordx4 v[12:15], v48, s[6:7]
	s_add_i32 s2, s15, 32
	s_lshl_b32 s3, s2, 8
	s_lshl_b32 s16, s14, 21
	s_add_u32 s16, s16, s3
	s_add_u32 s16, s16, 0x14000000
	s_add_u32 s6, s4, s16
	s_addc_u32 s7, s5, 0
	global_load_dwordx4 v[16:19], v48, s[6:7]
	s_add_u32 s6, s6, 0x80000
	s_addc_u32 s7, s7, 0
	global_load_dwordx4 v[20:23], v48, s[6:7]
	s_add_u32 s6, s6, 0x80000
	s_addc_u32 s7, s7, 0
	global_load_dwordx4 v[24:27], v48, s[6:7]
	s_add_u32 s6, s6, 0x80000
	s_addc_u32 s7, s7, 0
	global_load_dwordx4 v[28:31], v48, s[6:7]
	s_waitcnt vmcnt(4)
	ds_write_b128 v56, v[0:3]
	ds_write_b128 v57, v[4:7]
	ds_write_b128 v58, v[8:11]
	ds_write_b128 v59, v[12:15]
	s_add_i32 s2, s15, 0
	s_lshl_b32 s3, s2, 8
	s_lshl_b32 s16, s14, 21
	s_add_u32 s16, s16, s3
	s_add_u32 s16, s16, 0x15000000
	s_add_u32 s6, s4, s16
	s_addc_u32 s7, s5, 0
	global_load_dwordx4 v[0:3], v48, s[6:7]
	s_add_u32 s6, s6, 0x80000
	s_addc_u32 s7, s7, 0
	global_load_dwordx4 v[4:7], v48, s[6:7]
	s_add_u32 s6, s6, 0x80000
	s_addc_u32 s7, s7, 0
	global_load_dwordx4 v[8:11], v48, s[6:7]
	s_add_u32 s6, s6, 0x80000
	s_addc_u32 s7, s7, 0
	global_load_dwordx4 v[12:15], v48, s[6:7]
	s_waitcnt lgkmcnt(0)
	s_barrier
	s_add_i32 s2, s15, 0
	s_lshl_b32 s3, s2, 18
	s_lshl_b32 s16, s14, 8
	s_add_u32 s16, s16, s3
	s_add_u32 s16, s16, 0xc000000
	s_add_u32 s8, s4, s16
	s_addc_u32 s9, s5, 0
	ds_read2st64_b32 v[32:33], v60 offset0:0 offset1:1
	ds_read2st64_b32 v[34:35], v60 offset0:2 offset1:3
	ds_read2st64_b32 v[36:37], v60 offset0:4 offset1:5
	ds_read2st64_b32 v[38:39], v60 offset0:6 offset1:7
	s_waitcnt lgkmcnt(0)
	v_perm_b32 v40, v33, v32, s12
	v_perm_b32 v44, v33, v32, s13
	v_perm_b32 v41, v35, v34, s12
	v_perm_b32 v45, v35, v34, s13
	v_perm_b32 v42, v37, v36, s12
	v_perm_b32 v46, v37, v36, s13
	v_perm_b32 v43, v39, v38, s12
	v_perm_b32 v47, v39, v38, s13
	global_store_dwordx4 v62, v[40:43], s[8:9]
	global_store_dwordx4 v62, v[44:47], s[8:9] offset:2048
	ds_read2st64_b32 v[32:33], v61 offset0:0 offset1:1
	ds_read2st64_b32 v[34:35], v61 offset0:2 offset1:3
	ds_read2st64_b32 v[36:37], v61 offset0:4 offset1:5
	ds_read2st64_b32 v[38:39], v61 offset0:6 offset1:7
	s_add_u32 s8, s8, 0x20000
	s_addc_u32 s9, s9, 0
	s_waitcnt lgkmcnt(0)
	v_perm_b32 v40, v33, v32, s12
	v_perm_b32 v44, v33, v32, s13
	v_perm_b32 v41, v35, v34, s12
	v_perm_b32 v45, v35, v34, s13
	v_perm_b32 v42, v37, v36, s12
	v_perm_b32 v46, v37, v36, s13
	v_perm_b32 v43, v39, v38, s12
	v_perm_b32 v47, v39, v38, s13
	global_store_dwordx4 v62, v[40:43], s[8:9]
	global_store_dwordx4 v62, v[44:47], s[8:9] offset:2048
	s_waitcnt vmcnt(8)
	ds_write_b128 v56, v[16:19] offset:32768
	ds_write_b128 v57, v[20:23] offset:32768
	ds_write_b128 v58, v[24:27] offset:32768
	ds_write_b128 v59, v[28:31] offset:32768
	s_add_i32 s2, s15, 32
	s_lshl_b32 s3, s2, 8
	s_lshl_b32 s16, s14, 21
	s_add_u32 s16, s16, s3
	s_add_u32 s16, s16, 0x15000000
	s_add_u32 s6, s4, s16
	s_addc_u32 s7, s5, 0
	global_load_dwordx4 v[16:19], v48, s[6:7]
	s_add_u32 s6, s6, 0x80000
	s_addc_u32 s7, s7, 0
	global_load_dwordx4 v[20:23], v48, s[6:7]
	s_add_u32 s6, s6, 0x80000
	s_addc_u32 s7, s7, 0
	global_load_dwordx4 v[24:27], v48, s[6:7]
	s_add_u32 s6, s6, 0x80000
	s_addc_u32 s7, s7, 0
	global_load_dwordx4 v[28:31], v48, s[6:7]
	s_waitcnt lgkmcnt(0)
	s_barrier
	s_add_i32 s2, s15, 32
	s_lshl_b32 s3, s2, 18
	s_lshl_b32 s16, s14, 8
	s_add_u32 s16, s16, s3
	s_add_u32 s16, s16, 0xc000000
	s_add_u32 s8, s4, s16
	s_addc_u32 s9, s5, 0
	ds_read2st64_b32 v[32:33], v60 offset0:128 offset1:129
	ds_read2st64_b32 v[34:35], v60 offset0:130 offset1:131
	ds_read2st64_b32 v[36:37], v60 offset0:132 offset1:133
	ds_read2st64_b32 v[38:39], v60 offset0:134 offset1:135
	s_waitcnt lgkmcnt(0)
	v_perm_b32 v40, v33, v32, s12
	v_perm_b32 v44, v33, v32, s13
	v_perm_b32 v41, v35, v34, s12
	v_perm_b32 v45, v35, v34, s13
	v_perm_b32 v42, v37, v36, s12
	v_perm_b32 v46, v37, v36, s13
	v_perm_b32 v43, v39, v38, s12
	v_perm_b32 v47, v39, v38, s13
	global_store_dwordx4 v62, v[40:43], s[8:9]
	global_store_dwordx4 v62, v[44:47], s[8:9] offset:2048
	ds_read2st64_b32 v[32:33], v61 offset0:128 offset1:129
	ds_read2st64_b32 v[34:35], v61 offset0:130 offset1:131
	ds_read2st64_b32 v[36:37], v61 offset0:132 offset1:133
	ds_read2st64_b32 v[38:39], v61 offset0:134 offset1:135
	s_add_u32 s8, s8, 0x20000
	s_addc_u32 s9, s9, 0
	s_waitcnt lgkmcnt(0)
	v_perm_b32 v40, v33, v32, s12
	v_perm_b32 v44, v33, v32, s13
	v_perm_b32 v41, v35, v34, s12
	v_perm_b32 v45, v35, v34, s13
	v_perm_b32 v42, v37, v36, s12
	v_perm_b32 v46, v37, v36, s13
	v_perm_b32 v43, v39, v38, s12
	v_perm_b32 v47, v39, v38, s13
	global_store_dwordx4 v62, v[40:43], s[8:9]
	global_store_dwordx4 v62, v[44:47], s[8:9] offset:2048
	s_waitcnt vmcnt(12)
	ds_write_b128 v56, v[0:3]
	ds_write_b128 v57, v[4:7]
	ds_write_b128 v58, v[8:11]
	ds_write_b128 v59, v[12:15]
	s_add_i32 s2, s15, 0
	s_lshl_b32 s3, s2, 8
	s_lshl_b32 s16, s14, 21
	s_add_u32 s16, s16, s3
	s_add_u32 s16, s16, 0x16000000
	s_add_u32 s6, s4, s16
	s_addc_u32 s7, s5, 0
	global_load_dwordx4 v[0:3], v48, s[6:7]
	s_add_u32 s6, s6, 0x80000
	s_addc_u32 s7, s7, 0
	global_load_dwordx4 v[4:7], v48, s[6:7]
	s_add_u32 s6, s6, 0x80000
	s_addc_u32 s7, s7, 0
	global_load_dwordx4 v[8:11], v48, s[6:7]
	s_add_u32 s6, s6, 0x80000
	s_addc_u32 s7, s7, 0
	global_load_dwordx4 v[12:15], v48, s[6:7]
	s_waitcnt lgkmcnt(0)
	s_barrier
	s_add_i32 s2, s15, 0
	s_lshl_b32 s3, s2, 18
	s_lshl_b32 s16, s14, 8
	s_add_u32 s16, s16, s3
	s_add_u32 s16, s16, 0xd000000
	s_add_u32 s8, s4, s16
	s_addc_u32 s9, s5, 0
	ds_read2st64_b32 v[32:33], v60 offset0:0 offset1:1
	ds_read2st64_b32 v[34:35], v60 offset0:2 offset1:3
	ds_read2st64_b32 v[36:37], v60 offset0:4 offset1:5
	ds_read2st64_b32 v[38:39], v60 offset0:6 offset1:7
	s_waitcnt lgkmcnt(0)
	v_perm_b32 v40, v33, v32, s12
	v_perm_b32 v44, v33, v32, s13
	v_perm_b32 v41, v35, v34, s12
	v_perm_b32 v45, v35, v34, s13
	v_perm_b32 v42, v37, v36, s12
	v_perm_b32 v46, v37, v36, s13
	v_perm_b32 v43, v39, v38, s12
	v_perm_b32 v47, v39, v38, s13
	global_store_dwordx4 v62, v[40:43], s[8:9]
	global_store_dwordx4 v62, v[44:47], s[8:9] offset:2048
	ds_read2st64_b32 v[32:33], v61 offset0:0 offset1:1
	ds_read2st64_b32 v[34:35], v61 offset0:2 offset1:3
	ds_read2st64_b32 v[36:37], v61 offset0:4 offset1:5
	ds_read2st64_b32 v[38:39], v61 offset0:6 offset1:7
	s_add_u32 s8, s8, 0x20000
	s_addc_u32 s9, s9, 0
	s_waitcnt lgkmcnt(0)
	v_perm_b32 v40, v33, v32, s12
	v_perm_b32 v44, v33, v32, s13
	v_perm_b32 v41, v35, v34, s12
	v_perm_b32 v45, v35, v34, s13
	v_perm_b32 v42, v37, v36, s12
	v_perm_b32 v46, v37, v36, s13
	v_perm_b32 v43, v39, v38, s12
	v_perm_b32 v47, v39, v38, s13
	global_store_dwordx4 v62, v[40:43], s[8:9]
	global_store_dwordx4 v62, v[44:47], s[8:9] offset:2048
	s_waitcnt vmcnt(12)
	ds_write_b128 v56, v[16:19] offset:32768
	ds_write_b128 v57, v[20:23] offset:32768
	ds_write_b128 v58, v[24:27] offset:32768
	ds_write_b128 v59, v[28:31] offset:32768
	s_add_i32 s2, s15, 32
	s_lshl_b32 s3, s2, 8
	s_lshl_b32 s16, s14, 21
	s_add_u32 s16, s16, s3
	s_add_u32 s16, s16, 0x16000000
	s_add_u32 s6, s4, s16
	s_addc_u32 s7, s5, 0
	global_load_dwordx4 v[16:19], v48, s[6:7]
	s_add_u32 s6, s6, 0x80000
	s_addc_u32 s7, s7, 0
	global_load_dwordx4 v[20:23], v48, s[6:7]
	s_add_u32 s6, s6, 0x80000
	s_addc_u32 s7, s7, 0
	global_load_dwordx4 v[24:27], v48, s[6:7]
	s_add_u32 s6, s6, 0x80000
	s_addc_u32 s7, s7, 0
	global_load_dwordx4 v[28:31], v48, s[6:7]
	s_waitcnt lgkmcnt(0)
	s_barrier
	s_add_i32 s2, s15, 32
	s_lshl_b32 s3, s2, 18
	s_lshl_b32 s16, s14, 8
	s_add_u32 s16, s16, s3
	s_add_u32 s16, s16, 0xd000000
	s_add_u32 s8, s4, s16
	s_addc_u32 s9, s5, 0
	ds_read2st64_b32 v[32:33], v60 offset0:128 offset1:129
	ds_read2st64_b32 v[34:35], v60 offset0:130 offset1:131
	ds_read2st64_b32 v[36:37], v60 offset0:132 offset1:133
	ds_read2st64_b32 v[38:39], v60 offset0:134 offset1:135
	s_waitcnt lgkmcnt(0)
	v_perm_b32 v40, v33, v32, s12
	v_perm_b32 v44, v33, v32, s13
	v_perm_b32 v41, v35, v34, s12
	v_perm_b32 v45, v35, v34, s13
	v_perm_b32 v42, v37, v36, s12
	v_perm_b32 v46, v37, v36, s13
	v_perm_b32 v43, v39, v38, s12
	v_perm_b32 v47, v39, v38, s13
	global_store_dwordx4 v62, v[40:43], s[8:9]
	global_store_dwordx4 v62, v[44:47], s[8:9] offset:2048
	ds_read2st64_b32 v[32:33], v61 offset0:128 offset1:129
	ds_read2st64_b32 v[34:35], v61 offset0:130 offset1:131
	ds_read2st64_b32 v[36:37], v61 offset0:132 offset1:133
	ds_read2st64_b32 v[38:39], v61 offset0:134 offset1:135
	s_add_u32 s8, s8, 0x20000
	s_addc_u32 s9, s9, 0
	s_waitcnt lgkmcnt(0)
	v_perm_b32 v40, v33, v32, s12
	v_perm_b32 v44, v33, v32, s13
	v_perm_b32 v41, v35, v34, s12
	v_perm_b32 v45, v35, v34, s13
	v_perm_b32 v42, v37, v36, s12
	v_perm_b32 v46, v37, v36, s13
	v_perm_b32 v43, v39, v38, s12
	v_perm_b32 v47, v39, v38, s13
	global_store_dwordx4 v62, v[40:43], s[8:9]
	global_store_dwordx4 v62, v[44:47], s[8:9] offset:2048
	s_waitcnt vmcnt(12)
	ds_write_b128 v56, v[0:3]
	ds_write_b128 v57, v[4:7]
	ds_write_b128 v58, v[8:11]
	ds_write_b128 v59, v[12:15]
	s_add_i32 s2, s15, 0
	s_lshl_b32 s3, s2, 8
	s_lshl_b32 s16, s14, 21
	s_add_u32 s16, s16, s3
	s_add_u32 s16, s16, 0x17000000
	s_add_u32 s6, s4, s16
	s_addc_u32 s7, s5, 0
	global_load_dwordx4 v[0:3], v48, s[6:7]
	s_add_u32 s6, s6, 0x80000
	s_addc_u32 s7, s7, 0
	global_load_dwordx4 v[4:7], v48, s[6:7]
	s_add_u32 s6, s6, 0x80000
	s_addc_u32 s7, s7, 0
	global_load_dwordx4 v[8:11], v48, s[6:7]
	s_add_u32 s6, s6, 0x80000
	s_addc_u32 s7, s7, 0
	global_load_dwordx4 v[12:15], v48, s[6:7]
	s_waitcnt lgkmcnt(0)
	s_barrier
	s_add_i32 s2, s15, 0
	s_lshl_b32 s3, s2, 18
	s_lshl_b32 s16, s14, 8
	s_add_u32 s16, s16, s3
	s_add_u32 s16, s16, 0xe000000
	s_add_u32 s8, s4, s16
	s_addc_u32 s9, s5, 0
	ds_read2st64_b32 v[32:33], v60 offset0:0 offset1:1
	ds_read2st64_b32 v[34:35], v60 offset0:2 offset1:3
	ds_read2st64_b32 v[36:37], v60 offset0:4 offset1:5
	ds_read2st64_b32 v[38:39], v60 offset0:6 offset1:7
	s_waitcnt lgkmcnt(0)
	v_perm_b32 v40, v33, v32, s12
	v_perm_b32 v44, v33, v32, s13
	v_perm_b32 v41, v35, v34, s12
	v_perm_b32 v45, v35, v34, s13
	v_perm_b32 v42, v37, v36, s12
	v_perm_b32 v46, v37, v36, s13
	v_perm_b32 v43, v39, v38, s12
	v_perm_b32 v47, v39, v38, s13
	global_store_dwordx4 v62, v[40:43], s[8:9]
	global_store_dwordx4 v62, v[44:47], s[8:9] offset:2048
	ds_read2st64_b32 v[32:33], v61 offset0:0 offset1:1
	ds_read2st64_b32 v[34:35], v61 offset0:2 offset1:3
	ds_read2st64_b32 v[36:37], v61 offset0:4 offset1:5
	ds_read2st64_b32 v[38:39], v61 offset0:6 offset1:7
	s_add_u32 s8, s8, 0x20000
	s_addc_u32 s9, s9, 0
	s_waitcnt lgkmcnt(0)
	v_perm_b32 v40, v33, v32, s12
	v_perm_b32 v44, v33, v32, s13
	v_perm_b32 v41, v35, v34, s12
	v_perm_b32 v45, v35, v34, s13
	v_perm_b32 v42, v37, v36, s12
	v_perm_b32 v46, v37, v36, s13
	v_perm_b32 v43, v39, v38, s12
	v_perm_b32 v47, v39, v38, s13
	global_store_dwordx4 v62, v[40:43], s[8:9]
	global_store_dwordx4 v62, v[44:47], s[8:9] offset:2048
	s_waitcnt vmcnt(12)
	ds_write_b128 v56, v[16:19] offset:32768
	ds_write_b128 v57, v[20:23] offset:32768
	ds_write_b128 v58, v[24:27] offset:32768
	ds_write_b128 v59, v[28:31] offset:32768
	s_add_i32 s2, s15, 32
	s_lshl_b32 s3, s2, 8
	s_lshl_b32 s16, s14, 21
	s_add_u32 s16, s16, s3
	s_add_u32 s16, s16, 0x17000000
	s_add_u32 s6, s4, s16
	s_addc_u32 s7, s5, 0
	global_load_dwordx4 v[16:19], v48, s[6:7]
	s_add_u32 s6, s6, 0x80000
	s_addc_u32 s7, s7, 0
	global_load_dwordx4 v[20:23], v48, s[6:7]
	s_add_u32 s6, s6, 0x80000
	s_addc_u32 s7, s7, 0
	global_load_dwordx4 v[24:27], v48, s[6:7]
	s_add_u32 s6, s6, 0x80000
	s_addc_u32 s7, s7, 0
	global_load_dwordx4 v[28:31], v48, s[6:7]
	s_waitcnt lgkmcnt(0)
	s_barrier
	s_add_i32 s2, s15, 32
	s_lshl_b32 s3, s2, 18
	s_lshl_b32 s16, s14, 8
	s_add_u32 s16, s16, s3
	s_add_u32 s16, s16, 0xe000000
	s_add_u32 s8, s4, s16
	s_addc_u32 s9, s5, 0
	ds_read2st64_b32 v[32:33], v60 offset0:128 offset1:129
	ds_read2st64_b32 v[34:35], v60 offset0:130 offset1:131
	ds_read2st64_b32 v[36:37], v60 offset0:132 offset1:133
	ds_read2st64_b32 v[38:39], v60 offset0:134 offset1:135
	s_waitcnt lgkmcnt(0)
	v_perm_b32 v40, v33, v32, s12
	v_perm_b32 v44, v33, v32, s13
	v_perm_b32 v41, v35, v34, s12
	v_perm_b32 v45, v35, v34, s13
	v_perm_b32 v42, v37, v36, s12
	v_perm_b32 v46, v37, v36, s13
	v_perm_b32 v43, v39, v38, s12
	v_perm_b32 v47, v39, v38, s13
	global_store_dwordx4 v62, v[40:43], s[8:9]
	global_store_dwordx4 v62, v[44:47], s[8:9] offset:2048
	ds_read2st64_b32 v[32:33], v61 offset0:128 offset1:129
	ds_read2st64_b32 v[34:35], v61 offset0:130 offset1:131
	ds_read2st64_b32 v[36:37], v61 offset0:132 offset1:133
	ds_read2st64_b32 v[38:39], v61 offset0:134 offset1:135
	s_add_u32 s8, s8, 0x20000
	s_addc_u32 s9, s9, 0
	s_waitcnt lgkmcnt(0)
	v_perm_b32 v40, v33, v32, s12
	v_perm_b32 v44, v33, v32, s13
	v_perm_b32 v41, v35, v34, s12
	v_perm_b32 v45, v35, v34, s13
	v_perm_b32 v42, v37, v36, s12
	v_perm_b32 v46, v37, v36, s13
	v_perm_b32 v43, v39, v38, s12
	v_perm_b32 v47, v39, v38, s13
	global_store_dwordx4 v62, v[40:43], s[8:9]
	global_store_dwordx4 v62, v[44:47], s[8:9] offset:2048
	s_waitcnt vmcnt(12)
	ds_write_b128 v56, v[0:3]
	ds_write_b128 v57, v[4:7]
	ds_write_b128 v58, v[8:11]
	ds_write_b128 v59, v[12:15]
	s_waitcnt lgkmcnt(0)
	s_barrier
	s_add_i32 s2, s15, 0
	s_lshl_b32 s3, s2, 18
	s_lshl_b32 s16, s14, 8
	s_add_u32 s16, s16, s3
	s_add_u32 s16, s16, 0xf000000
	s_add_u32 s8, s4, s16
	s_addc_u32 s9, s5, 0
	ds_read2st64_b32 v[32:33], v60 offset0:0 offset1:1
	ds_read2st64_b32 v[34:35], v60 offset0:2 offset1:3
	ds_read2st64_b32 v[36:37], v60 offset0:4 offset1:5
	ds_read2st64_b32 v[38:39], v60 offset0:6 offset1:7
	s_waitcnt lgkmcnt(0)
	v_perm_b32 v40, v33, v32, s12
	v_perm_b32 v44, v33, v32, s13
	v_perm_b32 v41, v35, v34, s12
	v_perm_b32 v45, v35, v34, s13
	v_perm_b32 v42, v37, v36, s12
	v_perm_b32 v46, v37, v36, s13
	v_perm_b32 v43, v39, v38, s12
	v_perm_b32 v47, v39, v38, s13
	global_store_dwordx4 v62, v[40:43], s[8:9]
	global_store_dwordx4 v62, v[44:47], s[8:9] offset:2048
	ds_read2st64_b32 v[32:33], v61 offset0:0 offset1:1
	ds_read2st64_b32 v[34:35], v61 offset0:2 offset1:3
	ds_read2st64_b32 v[36:37], v61 offset0:4 offset1:5
	ds_read2st64_b32 v[38:39], v61 offset0:6 offset1:7
	s_add_u32 s8, s8, 0x20000
	s_addc_u32 s9, s9, 0
	s_waitcnt lgkmcnt(0)
	v_perm_b32 v40, v33, v32, s12
	v_perm_b32 v44, v33, v32, s13
	v_perm_b32 v41, v35, v34, s12
	v_perm_b32 v45, v35, v34, s13
	v_perm_b32 v42, v37, v36, s12
	v_perm_b32 v46, v37, v36, s13
	v_perm_b32 v43, v39, v38, s12
	v_perm_b32 v47, v39, v38, s13
	global_store_dwordx4 v62, v[40:43], s[8:9]
	global_store_dwordx4 v62, v[44:47], s[8:9] offset:2048
	s_waitcnt vmcnt(8)
	ds_write_b128 v56, v[16:19] offset:32768
	ds_write_b128 v57, v[20:23] offset:32768
	ds_write_b128 v58, v[24:27] offset:32768
	ds_write_b128 v59, v[28:31] offset:32768
	s_waitcnt lgkmcnt(0)
	s_barrier
	s_add_i32 s2, s15, 32
	s_lshl_b32 s3, s2, 18
	s_lshl_b32 s16, s14, 8
	s_add_u32 s16, s16, s3
	s_add_u32 s16, s16, 0xf000000
	s_add_u32 s8, s4, s16
	s_addc_u32 s9, s5, 0
	ds_read2st64_b32 v[32:33], v60 offset0:128 offset1:129
	ds_read2st64_b32 v[34:35], v60 offset0:130 offset1:131
	ds_read2st64_b32 v[36:37], v60 offset0:132 offset1:133
	ds_read2st64_b32 v[38:39], v60 offset0:134 offset1:135
	s_waitcnt lgkmcnt(0)
	v_perm_b32 v40, v33, v32, s12
	v_perm_b32 v44, v33, v32, s13
	v_perm_b32 v41, v35, v34, s12
	v_perm_b32 v45, v35, v34, s13
	v_perm_b32 v42, v37, v36, s12
	v_perm_b32 v46, v37, v36, s13
	v_perm_b32 v43, v39, v38, s12
	v_perm_b32 v47, v39, v38, s13
	global_store_dwordx4 v62, v[40:43], s[8:9]
	global_store_dwordx4 v62, v[44:47], s[8:9] offset:2048
	ds_read2st64_b32 v[32:33], v61 offset0:128 offset1:129
	ds_read2st64_b32 v[34:35], v61 offset0:130 offset1:131
	ds_read2st64_b32 v[36:37], v61 offset0:132 offset1:133
	ds_read2st64_b32 v[38:39], v61 offset0:134 offset1:135
	s_add_u32 s8, s8, 0x20000
	s_addc_u32 s9, s9, 0
	s_waitcnt lgkmcnt(0)
	v_perm_b32 v40, v33, v32, s12
	v_perm_b32 v44, v33, v32, s13
	v_perm_b32 v41, v35, v34, s12
	v_perm_b32 v45, v35, v34, s13
	v_perm_b32 v42, v37, v36, s12
	v_perm_b32 v46, v37, v36, s13
	v_perm_b32 v43, v39, v38, s12
	v_perm_b32 v47, v39, v38, s13
	global_store_dwordx4 v62, v[40:43], s[8:9]
	global_store_dwordx4 v62, v[44:47], s[8:9] offset:2048
